# 32x32x16 attention loop: per 16-key step the 6 MFMAs issue back to back, then the exp/add/cvt block
# baseline (speedup 1.0000x reference)
.Lattn_nf_loop:
	s_and_b32 s10, s15, 1
	s_mul_i32 s6, s10, 0x8800
	v_add_u32_e32 v136, s6, v137
	v_add_u32_e32 v170, s6, v183
	s_sub_u32 s10, 0x8800, s6
	ds_read_b128 v[98:101], v136 offset:0
	ds_read_b128 v[102:105], v136 offset:32
	ds_read_b128 v[106:109], v136 offset:64
	ds_read_b128 v[110:113], v136 offset:96
	v_add_u32_e32 v171, s10, v126
	v_add_u32_e32 v173, s10, v127
	global_load_dwordx4 v[82:85], v124, s[64:65]
	global_load_dwordx4 v[86:89], v124, s[66:67]
	global_load_dwordx4 v[90:93], v124, s[68:69]
	global_load_dwordx4 v[94:97], v124, s[70:71]
	v_add_u32_e32 v124, s36, v124
	s_waitcnt lgkmcnt(3)
	v_mfma_f32_32x32x16_bf16 v[138:153], v[98:101], v[10:13], 0
	ds_read_b128 v[98:101], v136 offset:8704
	s_waitcnt lgkmcnt(3)
	v_mfma_f32_32x32x16_bf16 v[138:153], v[102:105], v[14:17], v[138:153]
	ds_read_b128 v[102:105], v136 offset:8736
	s_waitcnt lgkmcnt(3)
	v_mfma_f32_32x32x16_bf16 v[138:153], v[106:109], v[2:5], v[138:153]
	ds_read_b128 v[106:109], v136 offset:8768
	s_waitcnt lgkmcnt(3)
	v_mfma_f32_32x32x16_bf16 v[138:153], v[110:113], v[6:9], v[138:153]
	ds_read_b128 v[110:113], v136 offset:8800
	ds_read_b128 v[128:131], v170 offset:0
	ds_read_b128 v[184:187], v170 offset:8704
	ds_read_b128 v[188:191], v170 offset:17408
	ds_read_b128 v[192:195], v170 offset:26112
	s_waitcnt lgkmcnt(7)
	v_mfma_f32_32x32x16_bf16 v[154:169], v[98:101], v[10:13], 0
	ds_read_b128 v[98:101], v136 offset:17408
	s_waitcnt lgkmcnt(7)
	v_mfma_f32_32x32x16_bf16 v[154:169], v[102:105], v[14:17], v[154:169]
	ds_read_b128 v[102:105], v136 offset:17440
	s_nop 0
	v_exp_f32_e32 v138, v138
	v_exp_f32_e32 v139, v139
	v_exp_f32_e32 v140, v140
	v_exp_f32_e32 v141, v141
	v_exp_f32_e32 v142, v142
	v_exp_f32_e32 v143, v143
	v_exp_f32_e32 v144, v144
	v_exp_f32_e32 v145, v145
	v_add_f32_e32 v122, v138, v122
	v_add_f32_e32 v122, v139, v122
	v_add_f32_e32 v122, v140, v122
	v_add_f32_e32 v122, v141, v122
	v_add_f32_e32 v122, v142, v122
	v_add_f32_e32 v122, v143, v122
	v_add_f32_e32 v122, v144, v122
	v_add_f32_e32 v122, v145, v122
	v_cvt_pk_bf16_f32 v114, v138, v139
	v_cvt_pk_bf16_f32 v115, v140, v141
	v_cvt_pk_bf16_f32 v116, v142, v143
	v_cvt_pk_bf16_f32 v117, v144, v145
	ds_read_b128 v[196:199], v170 offset:32
	ds_read_b128 v[216:219], v170 offset:8736
	ds_read_b128 v[200:203], v170 offset:17440
	ds_read_b128 v[204:207], v170 offset:26144
	s_waitcnt lgkmcnt(11)
	v_mfma_f32_32x32x16_bf16 v[154:169], v[106:109], v[2:5], v[154:169]
	ds_read_b128 v[106:109], v136 offset:17472
	s_waitcnt lgkmcnt(11)
	v_mfma_f32_32x32x16_bf16 v[154:169], v[110:113], v[6:9], v[154:169]
	ds_read_b128 v[110:113], v136 offset:17504
	s_waitcnt lgkmcnt(11)
	v_mfma_f32_32x32x16_bf16 v[18:33], v[128:131], v[114:117], v[18:33]
	s_waitcnt lgkmcnt(10)
	v_mfma_f32_32x32x16_bf16 v[34:49], v[184:187], v[114:117], v[34:49]
	s_waitcnt lgkmcnt(9)
	v_mfma_f32_32x32x16_bf16 v[50:65], v[188:191], v[114:117], v[50:65]
	s_waitcnt lgkmcnt(8)
	v_mfma_f32_32x32x16_bf16 v[66:81], v[192:195], v[114:117], v[66:81]
	v_exp_f32_e32 v146, v146
	v_exp_f32_e32 v147, v147
	v_exp_f32_e32 v148, v148
	v_exp_f32_e32 v149, v149
	v_exp_f32_e32 v150, v150
	v_exp_f32_e32 v151, v151
	v_exp_f32_e32 v152, v152
	v_exp_f32_e32 v153, v153
	v_add_f32_e32 v122, v146, v122
	v_add_f32_e32 v122, v147, v122
	v_add_f32_e32 v122, v148, v122
	v_add_f32_e32 v122, v149, v122
	v_add_f32_e32 v122, v150, v122
	v_add_f32_e32 v122, v151, v122
	v_add_f32_e32 v122, v152, v122
	v_add_f32_e32 v122, v153, v122
	v_cvt_pk_bf16_f32 v118, v146, v147
	v_cvt_pk_bf16_f32 v119, v148, v149
	v_cvt_pk_bf16_f32 v120, v150, v151
	v_cvt_pk_bf16_f32 v121, v152, v153
	ds_read_b128 v[128:131], v170 offset:64
	ds_read_b128 v[184:187], v170 offset:8768
	ds_read_b128 v[188:191], v170 offset:17472
	ds_read_b128 v[192:195], v170 offset:26176
	s_waitcnt lgkmcnt(11)
	v_mfma_f32_32x32x16_bf16 v[138:153], v[98:101], v[10:13], 0
	ds_read_b128 v[98:101], v136 offset:26112
	s_waitcnt lgkmcnt(11)
	v_mfma_f32_32x32x16_bf16 v[138:153], v[102:105], v[14:17], v[138:153]
	ds_read_b128 v[102:105], v136 offset:26144
	s_waitcnt lgkmcnt(11)
	v_mfma_f32_32x32x16_bf16 v[18:33], v[196:199], v[118:121], v[18:33]
	s_waitcnt lgkmcnt(10)
	v_mfma_f32_32x32x16_bf16 v[34:49], v[216:219], v[118:121], v[34:49]
	s_waitcnt lgkmcnt(9)
	v_mfma_f32_32x32x16_bf16 v[50:65], v[200:203], v[118:121], v[50:65]
	s_waitcnt lgkmcnt(8)
	v_mfma_f32_32x32x16_bf16 v[66:81], v[204:207], v[118:121], v[66:81]
	v_exp_f32_e32 v154, v154
	v_exp_f32_e32 v155, v155
	v_exp_f32_e32 v156, v156
	v_exp_f32_e32 v157, v157
	v_exp_f32_e32 v158, v158
	v_exp_f32_e32 v159, v159
	v_exp_f32_e32 v160, v160
	v_exp_f32_e32 v161, v161
	v_add_f32_e32 v122, v154, v122
	v_add_f32_e32 v122, v155, v122
	v_add_f32_e32 v122, v156, v122
	v_add_f32_e32 v122, v157, v122
	v_add_f32_e32 v122, v158, v122
	v_add_f32_e32 v122, v159, v122
	v_add_f32_e32 v122, v160, v122
	v_add_f32_e32 v122, v161, v122
	v_cvt_pk_bf16_f32 v114, v154, v155
	v_cvt_pk_bf16_f32 v115, v156, v157
	v_cvt_pk_bf16_f32 v116, v158, v159
	v_cvt_pk_bf16_f32 v117, v160, v161
	ds_read_b128 v[196:199], v170 offset:96
	ds_read_b128 v[216:219], v170 offset:8800
	ds_read_b128 v[200:203], v170 offset:17504
	ds_read_b128 v[204:207], v170 offset:26208
	s_waitcnt lgkmcnt(11)
	v_mfma_f32_32x32x16_bf16 v[138:153], v[106:109], v[2:5], v[138:153]
	ds_read_b128 v[106:109], v136 offset:26176
	s_waitcnt lgkmcnt(11)
	v_mfma_f32_32x32x16_bf16 v[138:153], v[110:113], v[6:9], v[138:153]
	ds_read_b128 v[110:113], v136 offset:26208
	s_waitcnt lgkmcnt(11)
	v_mfma_f32_32x32x16_bf16 v[18:33], v[128:131], v[114:117], v[18:33]
	s_waitcnt lgkmcnt(10)
	v_mfma_f32_32x32x16_bf16 v[34:49], v[184:187], v[114:117], v[34:49]
	s_waitcnt lgkmcnt(9)
	v_mfma_f32_32x32x16_bf16 v[50:65], v[188:191], v[114:117], v[50:65]
	s_waitcnt lgkmcnt(8)
	v_mfma_f32_32x32x16_bf16 v[66:81], v[192:195], v[114:117], v[66:81]
	v_exp_f32_e32 v162, v162
	v_exp_f32_e32 v163, v163
	v_exp_f32_e32 v164, v164
	v_exp_f32_e32 v165, v165
	v_exp_f32_e32 v166, v166
	v_exp_f32_e32 v167, v167
	v_exp_f32_e32 v168, v168
	v_exp_f32_e32 v169, v169
	v_add_f32_e32 v122, v162, v122
	v_add_f32_e32 v122, v163, v122
	v_add_f32_e32 v122, v164, v122
	v_add_f32_e32 v122, v165, v122
	v_add_f32_e32 v122, v166, v122
	v_add_f32_e32 v122, v167, v122
	v_add_f32_e32 v122, v168, v122
	v_add_f32_e32 v122, v169, v122
	v_cvt_pk_bf16_f32 v118, v162, v163
	v_cvt_pk_bf16_f32 v119, v164, v165
	v_cvt_pk_bf16_f32 v120, v166, v167
	v_cvt_pk_bf16_f32 v121, v168, v169
	ds_read_b128 v[128:131], v170 offset:128
	ds_read_b128 v[184:187], v170 offset:8832
	ds_read_b128 v[188:191], v170 offset:17536
	ds_read_b128 v[192:195], v170 offset:26240
	s_waitcnt lgkmcnt(11)
	v_mfma_f32_32x32x16_bf16 v[154:169], v[98:101], v[10:13], 0
	s_waitcnt lgkmcnt(10)
	v_mfma_f32_32x32x16_bf16 v[154:169], v[102:105], v[14:17], v[154:169]
	s_waitcnt lgkmcnt(9)
	v_mfma_f32_32x32x16_bf16 v[18:33], v[196:199], v[118:121], v[18:33]
	s_waitcnt vmcnt(3)
	ds_write_b128 v171, v[82:85] offset:0
	s_waitcnt vmcnt(2)
	ds_write_b128 v171, v[86:89] offset:8704
	s_waitcnt vmcnt(1)
	ds_write_b128 v171, v[90:93] offset:17408
	s_waitcnt vmcnt(0)
	ds_write_b128 v171, v[94:97] offset:26112
	s_waitcnt lgkmcnt(12)
	v_mfma_f32_32x32x16_bf16 v[34:49], v[216:219], v[118:121], v[34:49]
	s_waitcnt lgkmcnt(11)
	v_mfma_f32_32x32x16_bf16 v[50:65], v[200:203], v[118:121], v[50:65]
	s_waitcnt lgkmcnt(10)
	v_mfma_f32_32x32x16_bf16 v[66:81], v[204:207], v[118:121], v[66:81]
	v_exp_f32_e32 v138, v138
	v_exp_f32_e32 v139, v139
	v_exp_f32_e32 v140, v140
	v_exp_f32_e32 v141, v141
	v_exp_f32_e32 v142, v142
	v_exp_f32_e32 v143, v143
	v_exp_f32_e32 v144, v144
	v_exp_f32_e32 v145, v145
	v_add_f32_e32 v122, v138, v122
	v_add_f32_e32 v122, v139, v122
	v_add_f32_e32 v122, v140, v122
	v_add_f32_e32 v122, v141, v122
	v_add_f32_e32 v122, v142, v122
	v_add_f32_e32 v122, v143, v122
	v_add_f32_e32 v122, v144, v122
	v_add_f32_e32 v122, v145, v122
	v_cvt_pk_bf16_f32 v114, v138, v139
	v_cvt_pk_bf16_f32 v115, v140, v141
	v_cvt_pk_bf16_f32 v116, v142, v143
	v_cvt_pk_bf16_f32 v117, v144, v145
	ds_read_b128 v[196:199], v170 offset:160
	ds_read_b128 v[216:219], v170 offset:8864
	ds_read_b128 v[200:203], v170 offset:17568
	ds_read_b128 v[204:207], v170 offset:26272
	s_waitcnt lgkmcnt(13)
	v_mfma_f32_32x32x16_bf16 v[154:169], v[106:109], v[2:5], v[154:169]
	s_waitcnt lgkmcnt(12)
	v_mfma_f32_32x32x16_bf16 v[154:169], v[110:113], v[6:9], v[154:169]
	s_waitcnt lgkmcnt(11)
	v_mfma_f32_32x32x16_bf16 v[18:33], v[128:131], v[114:117], v[18:33]
	global_load_dwordx4 v[82:85], v125, s[72:73]
	global_load_dwordx4 v[86:89], v125, s[74:75]
	global_load_dwordx4 v[90:93], v125, s[76:77]
	global_load_dwordx4 v[94:97], v125, s[78:79]
	v_add_u32_e32 v125, s38, v125
	s_waitcnt lgkmcnt(10)
	v_mfma_f32_32x32x16_bf16 v[34:49], v[184:187], v[114:117], v[34:49]
	s_waitcnt lgkmcnt(9)
	v_mfma_f32_32x32x16_bf16 v[50:65], v[188:191], v[114:117], v[50:65]
	s_waitcnt lgkmcnt(8)
	v_mfma_f32_32x32x16_bf16 v[66:81], v[192:195], v[114:117], v[66:81]
	v_exp_f32_e32 v146, v146
	v_exp_f32_e32 v147, v147
	v_exp_f32_e32 v148, v148
	v_exp_f32_e32 v149, v149
	v_exp_f32_e32 v150, v150
	v_exp_f32_e32 v151, v151
	v_exp_f32_e32 v152, v152
	v_exp_f32_e32 v153, v153
	v_add_f32_e32 v122, v146, v122
	v_add_f32_e32 v122, v147, v122
	v_add_f32_e32 v122, v148, v122
	v_add_f32_e32 v122, v149, v122
	v_add_f32_e32 v122, v150, v122
	v_add_f32_e32 v122, v151, v122
	v_add_f32_e32 v122, v152, v122
	v_add_f32_e32 v122, v153, v122
	v_cvt_pk_bf16_f32 v118, v146, v147
	v_cvt_pk_bf16_f32 v119, v148, v149
	v_cvt_pk_bf16_f32 v120, v150, v151
	v_cvt_pk_bf16_f32 v121, v152, v153
	ds_read_b128 v[128:131], v170 offset:192
	ds_read_b128 v[184:187], v170 offset:8896
	ds_read_b128 v[188:191], v170 offset:17600
	ds_read_b128 v[192:195], v170 offset:26304
	s_waitcnt lgkmcnt(7)
	v_mfma_f32_32x32x16_bf16 v[18:33], v[196:199], v[118:121], v[18:33]
	s_waitcnt lgkmcnt(6)
	v_mfma_f32_32x32x16_bf16 v[34:49], v[216:219], v[118:121], v[34:49]
	s_waitcnt lgkmcnt(5)
	v_mfma_f32_32x32x16_bf16 v[50:65], v[200:203], v[118:121], v[50:65]
	s_waitcnt lgkmcnt(4)
	v_mfma_f32_32x32x16_bf16 v[66:81], v[204:207], v[118:121], v[66:81]
	v_exp_f32_e32 v154, v154
	v_exp_f32_e32 v155, v155
	v_exp_f32_e32 v156, v156
	v_exp_f32_e32 v157, v157
	v_exp_f32_e32 v158, v158
	v_exp_f32_e32 v159, v159
	v_exp_f32_e32 v160, v160
	v_exp_f32_e32 v161, v161
	v_add_f32_e32 v122, v154, v122
	v_add_f32_e32 v122, v155, v122
	v_add_f32_e32 v122, v156, v122
	v_add_f32_e32 v122, v157, v122
	v_add_f32_e32 v122, v158, v122
	v_add_f32_e32 v122, v159, v122
	v_add_f32_e32 v122, v160, v122
	v_add_f32_e32 v122, v161, v122
	v_cvt_pk_bf16_f32 v114, v154, v155
	v_cvt_pk_bf16_f32 v115, v156, v157
	v_cvt_pk_bf16_f32 v116, v158, v159
	v_cvt_pk_bf16_f32 v117, v160, v161
	ds_read_b128 v[196:199], v170 offset:224
	ds_read_b128 v[216:219], v170 offset:8928
	ds_read_b128 v[200:203], v170 offset:17632
	ds_read_b128 v[204:207], v170 offset:26336
	s_waitcnt lgkmcnt(7)
	v_mfma_f32_32x32x16_bf16 v[18:33], v[128:131], v[114:117], v[18:33]
	s_waitcnt lgkmcnt(6)
	v_mfma_f32_32x32x16_bf16 v[34:49], v[184:187], v[114:117], v[34:49]
	s_waitcnt lgkmcnt(5)
	v_mfma_f32_32x32x16_bf16 v[50:65], v[188:191], v[114:117], v[50:65]
	s_waitcnt lgkmcnt(4)
	v_mfma_f32_32x32x16_bf16 v[66:81], v[192:195], v[114:117], v[66:81]
	v_exp_f32_e32 v162, v162
	v_exp_f32_e32 v163, v163
	v_exp_f32_e32 v164, v164
	v_exp_f32_e32 v165, v165
	v_exp_f32_e32 v166, v166
	v_exp_f32_e32 v167, v167
	v_exp_f32_e32 v168, v168
	v_exp_f32_e32 v169, v169
	v_add_f32_e32 v122, v162, v122
	v_add_f32_e32 v122, v163, v122
	v_add_f32_e32 v122, v164, v122
	v_add_f32_e32 v122, v165, v122
	v_add_f32_e32 v122, v166, v122
	v_add_f32_e32 v122, v167, v122
	v_add_f32_e32 v122, v168, v122
	v_add_f32_e32 v122, v169, v122
	v_cvt_pk_bf16_f32 v118, v162, v163
	v_cvt_pk_bf16_f32 v119, v164, v165
	v_cvt_pk_bf16_f32 v120, v166, v167
	v_cvt_pk_bf16_f32 v121, v168, v169
	s_waitcnt lgkmcnt(3)
	s_nop 0
	v_mfma_f32_32x32x16_bf16 v[18:33], v[196:199], v[118:121], v[18:33]
	s_waitcnt lgkmcnt(2)
	v_mfma_f32_32x32x16_bf16 v[34:49], v[216:219], v[118:121], v[34:49]
	s_waitcnt vmcnt(3)
	ds_write_b128 v173, v[82:85] offset:0
	s_waitcnt vmcnt(2)
	ds_write_b128 v173, v[86:89] offset:8704
	s_waitcnt vmcnt(1)
	ds_write_b128 v173, v[90:93] offset:17408
	s_waitcnt vmcnt(0)
	ds_write_b128 v173, v[94:97] offset:26112
	s_waitcnt lgkmcnt(5)
	v_mfma_f32_32x32x16_bf16 v[50:65], v[200:203], v[118:121], v[50:65]
	s_waitcnt lgkmcnt(4)
	v_mfma_f32_32x32x16_bf16 v[66:81], v[204:207], v[118:121], v[66:81]
	s_waitcnt lgkmcnt(0)
	s_barrier
	s_add_i32 s15, s15, 1
	s_cmp_eq_u32 s15, 34
	s_cbranch_scc0 .Lattn_nf_loop
	v_readlane_b32 s64, v175, 0
	v_readlane_b32 s65, v175, 1
	v_readlane_b32 s66, v175, 2
	v_readlane_b32 s67, v175, 3
	v_readlane_b32 s68, v175, 4
	v_readlane_b32 s69, v175, 5
	v_readlane_b32 s70, v175, 6
	v_readlane_b32 s71, v175, 7
	v_readlane_b32 s72, v175, 8
	v_readlane_b32 s73, v175, 9
	v_readlane_b32 s74, v175, 10
	v_readlane_b32 s75, v175, 11
	v_readlane_b32 s76, v175, 12
	v_readlane_b32 s77, v175, 13
	v_readlane_b32 s78, v175, 14
	v_readlane_b32 s79, v175, 15
	s_nop 4
	v_add_f32_e32 v186, v132, v134
	v_add_f32_e32 v184, v133, v135
	ds_bpermute_b32 v187, v172, v186
	ds_bpermute_b32 v185, v172, v184
	s_mov_b32 s10, 0x3fb8aa3b
	s_mov_b32 s11, 0xc2ce8ed0
	s_mov_b32 s6, 0x42b17218
	v_cmp_eq_u32_e64 s[40:41], 0, v179
	s_lshl_b32 s30, s14, 1
	v_lshlrev_b32_e32 v196, 3, v178
	v_mov_b32_e32 v197, 0
	v_lshlrev_b32_e32 v198, 4, v179
	v_or3_b32 v198, v198, v177, v180
	v_ashrrev_i32_e32 v199, 31, v198
	v_lshlrev_b64 v[198:199], 11, v[198:199]
	s_mov_b64 s[100:101], 0x18a10000
	v_lshl_add_u64 v[198:199], s[42:43], 0, v[198:199]
	v_lshl_add_u64 v[198:199], v[198:199], 0, s[30:31]
	v_lshl_add_u64 v[198:199], v[198:199], 0, v[196:197]
	v_lshl_add_u64 v[198:199], v[198:199], 0, s[100:101]
	global_load_dwordx2 v[146:147], v[198:199], off
	global_load_dwordx2 v[148:149], v[198:199], off offset:32
	global_load_dwordx2 v[150:151], v[198:199], off offset:64
	global_load_dwordx2 v[152:153], v[198:199], off offset:96
	global_load_dwordx2 v[188:189], v[198:199], off offset:128
	global_load_dwordx2 v[190:191], v[198:199], off offset:160
	global_load_dwordx2 v[192:193], v[198:199], off offset:192
	global_load_dwordx2 v[194:195], v[198:199], off offset:224
	s_mov_b64 s[100:101], exec
	s_and_b64 exec, exec, s[4:5]
	s_cbranch_execz .Lpop_skip
	v_readlane_b32 s14, v255, 22
	v_readlane_b32 s15, v255, 23
	v_mov_b32_e32 v224, 1
	s_nop 4
	global_atomic_add v224, v0, v224, s[14:15] sc0
